# prompt attention: one static s_setprio 1 for waves 4-7 (the younger half of every SIMD pair) for the whole attention section, reset at its exit
# baseline (speedup 1.0000x reference)
; template<int THRL,bool PART> __device__ __forceinline__ int attn_unit(const bf16*Qb,const bf16*__restrict__ Kh,const bf16*__restrict__ Vh,bf16*Ob,const int NT,const int vlim_in,char*shm,const int s0,const bool primed,const bf16*nKh,const bf16*nVh,bf16*fuseM,const float lam){
;   int tid=threadIdx.x; asm volatile("":"+v"(tid));
;   const int lane=tid&63,r32=lane&31,hi=lane>>5; const int wid=__builtin_amdgcn_readfirstlane(tid>>6);
;   const int vlim=(vlim_in<0)?(wid>>1):vlim_in;
;   const bool act=PART?(wid<2):true;
;   const bf16*Qw=Qb+(long)(wid*QBLK)*KP;
;   const unsigned lds0=(unsigned)(uintptr_t)shm;
;   float*wsf=(float*)(shm+LDS_WS)+wid*64;
;   const bf16*ksrc=Kh+(long)lane*KP+wid*8;
;   const bf16*vsrc=Vh+(long)(16*(wid&3)+(lane>>2))*KP+(wid>>2)*32+(lane&3)*8;
;   const unsigned kdst=lds0+LDS_K+wid*1024, vdst=lds0+LDS_V+wid*1024;
;     ...
;   const int vb0=(int)(lds0+LDS_V)+((lane>>4)&1)*32+(lane&3)*8+(4*hi+((lane&15)>>2))*64;
;   const int s1=(s0==(NSLOT-1)*SLOTB)?0:s0+SLOTB, s2=(s1==(NSLOT-1)*SLOTB)?0:s1+SLOTB;
;   const char*Kbase=shm+LDS_K+s0; bf16x8 kf[8];
;   const lds_cptr shm3=(lds_cptr)shm; const lds_cptr kp0=shm3+LDS_K+hi*1024+r32*16; const lds_cptr vp0=shm3+LDS_V+((lane>>4)&1)*32+(lane&3)*8+(4*hi+((lane&15)>>2))*64;
; __global__ void __launch_bounds__(NWAVES * 64, 2) mk_fwd(Args args) {
;     ...
;     if (IN(7)) { __syncthreads();
;         { const float lam = MISC[0];
;         for (int v = vcu; v < 256; v += G) {
;             const int bh = v >> 3, s = v & 7, b = bh >> 2, hd = bh & 3;
;             int ring0 = 0; bool primed = false;
;             for (int i = 0; i < 8; ++i) { const int qb = (i >> 2) ? 15 - s : s, j = (i >> 1) & 1, vh = i & 1;
;                 const bf16* Qp = Qb + (size_t)(b * 4096 + qb * 256) * 512 + (hd * 2 + j) * 64; const bf16* Kp = Kb + (size_t)(b * 4096) * 512 + (hd * 2 + j) * 64; const bf16* Vp = Vb + (size_t)(b * 4096) * 512 + (hd * 2 + vh) * 64;
.LBB0_925:
	s_cmpk_gt_i32 s92, 0xff
	s_waitcnt vmcnt(0) lgkmcnt(0)
	s_barrier
	s_cbranch_scc1 .LBB0_1021
	v_mov_b32_e32 v3, 0x1a0000
	global_load_dword v217, v3, s[66:67]
	v_and_b32_e32 v0, 63, v252
	v_and_b32_e32 v1, 31, v252
	v_bfe_u32 v2, v252, 5, 1
	v_lshrrev_b32_e32 v3, 6, v252
	s_nop 0
	v_readfirstlane_b32 s4, v3
	s_and_b32 s5, s4, 3
	s_lshr_b32 s6, s4, 2
	s_mov_b32 s48, 0x41000000
	s_xor_b32 s45, s4, 2
	s_cmp_lt_u32 s4, 4
	s_cselect_b32 s45, s4, s45
	s_and_b32 s46, s45, 3
	s_lshr_b32 s47, s45, 2
	s_cmp_ge_u32 s4, 4
	s_cbranch_scc0 .Lat_prio
	s_setprio 1
.Lat_prio:
	v_bfe_u32 v219, v1, 1, 3
	v_lshlrev_b32_e32 v220, 7, v1
	v_or_b32_e32 v221, 0, v2
	v_xor_b32_e32 v221, v221, v219
	v_lshl_add_u32 v235, v221, 4, v220
	v_or_b32_e32 v221, 2, v2
	v_xor_b32_e32 v221, v221, v219
	v_lshl_add_u32 v236, v221, 4, v220
	v_or_b32_e32 v221, 4, v2
	v_xor_b32_e32 v221, v221, v219
	v_lshl_add_u32 v237, v221, 4, v220
	v_or_b32_e32 v221, 6, v2
	v_xor_b32_e32 v221, v221, v219
	v_lshl_add_u32 v238, v221, 4, v220
	v_bfe_u32 v218, v0, 4, 1
	v_lshlrev_b32_e32 v229, 5, v218
	v_and_b32_e32 v218, 3, v0
	v_lshl_add_u32 v229, v218, 3, v229
	v_bfe_u32 v218, v0, 2, 2
	v_lshl_add_u32 v218, v2, 2, v218
	v_lshl_add_u32 v229, v218, 6, v229
	s_lshl_b32 s34, s4, 10
	s_add_i32 s34, s34, 0x18000
	v_mov_b32_e32 v230, s34
	v_lshlrev_b32_e32 v240, 2, v1
	v_lshlrev_b32_e32 v241, 4, v2
	v_lshrrev_b32_e32 v218, 3, v0
	s_lshl_b32 s34, s4, 3
	v_add_u32_e32 v218, s34, v218
	v_bfe_u32 v219, v218, 1, 3
	v_and_b32_e32 v220, 7, v0
	v_xor_b32_e32 v219, v219, v220
	v_lshlrev_b32_e32 v231, 10, v218
	v_lshl_add_u32 v231, v219, 4, v231
	v_lshrrev_b32_e32 v218, 2, v0
	v_lshlrev_b32_e32 v232, 10, v218
	v_and_b32_e32 v218, 3, v0
	v_lshl_add_u32 v232, v218, 4, v232
	s_lshl_b32 s34, s5, 14
	s_lshl_b32 s35, s6, 6
	s_add_i32 s34, s34, s35
	v_add_u32_e32 v232, s34, v232
	v_add_u32_e32 v233, 0x80, v232
	v_lshlrev_b32_e32 v234, 10, v1
	v_lshl_add_u32 v234, v2, 4, v234
	v_lshlrev_b32_e32 v239, 4, v0
	s_lshl_b32 s34, s92, 3
	s_add_i32 s34, s34, s4
	s_lshl_b32 s34, s34, 14
	s_add_u32 s52, s66, s34
	s_addc_u32 s53, s67, 0
	s_add_u32 s52, s52, 0x6f00000
	s_addc_u32 s53, s53, 0
	s_waitcnt vmcnt(0)
	v_readfirstlane_b32 s7, v217
	s_mov_b32 s8, s92

; __global__ void __launch_bounds__(NWAVES * 64, 2) mk_fwd(Args args) {
;     ...
;         for (int v = vcu; v < 256; v += G) {
;             const int bh = v >> 3, s = v & 7, b = bh >> 2, hd = bh & 3;
;             int ring0 = 0; bool primed = false;
;             for (int i = 0; i < 8; ++i) { const int qb = (i >> 2) ? 15 - s : s, j = (i >> 1) & 1, vh = i & 1;
;                 const bf16* Qp = Qb + (size_t)(b * 4096 + qb * 256) * 512 + (hd * 2 + j) * 64; const bf16* Kp = Kb + (size_t)(b * 4096) * 512 + (hd * 2 + j) * 64; const bf16* Vp = Vb + (size_t)(b * 4096) * 512 + (hd * 2 + vh) * 64;
;                 bf16* Op = ATTO + (size_t)(b * 4096 + qb * 256) * 1024 + ((hd * 2 + j) * 2 + vh) * 64;
;                 bf16* Mp = ((i & 3) == 3) ? H + (size_t)(b * 4096 + qb * 256) * 1024 + 512 + hd * 128 : nullptr;
;                 const bool more = i < 7; const int jn = ((i + 1) >> 1) & 1, vn = (i + 1) & 1;
;                 const bf16* nK = Kb + (size_t)(b * 4096) * 512 + (hd * 2 + jn) * 64; const bf16* nV = Vb + (size_t)(b * 4096) * 512 + (hd * 2 + vn) * 64;
;                 ring0 = attn_body::attn_unit<8, false>((const attn_body::bf16*)Qp, (const attn_body::bf16*)Kp, (const attn_body::bf16*)Vp, (attn_body::bf16*)Op, 4 * (qb + 1), -1, (char*)lds, ring0, primed,
;                                                        more ? (const attn_body::bf16*)nK : nullptr, more ? (const attn_body::bf16*)nV : nullptr, (attn_body::bf16*)Mp, lam); primed = more; }
;         } }
.Lat_udone12:
	s_barrier
	s_add_i32 s14, s14, 1
	s_cmp_lt_u32 s14, 2
	s_cbranch_scc1 .Lat_j
	s_add_i32 s12, s12, 1
	s_cmp_lt_u32 s12, 2
	s_cbranch_scc1 .Lat_blk
	s_add_i32 s8, s8, s69
	s_cmpk_gt_i32 s8, 0xff
	s_cbranch_scc0 .Lat_v
	s_setprio 0
	s_branch .LBB0_1021
